# drop the XCD meeting between attention and the elementwise phase (no data dependence); keep the workgroup barrier
# baseline (speedup 1.0000x reference)
; __device__ __forceinline__ unsigned xb_ld(unsigned* p)              { return __hip_atomic_load(p, __ATOMIC_RELAXED, __HIP_MEMORY_SCOPE_AGENT); }
; __device__ __forceinline__ unsigned xb_add(unsigned* p, unsigned v) { return __hip_atomic_fetch_add(p, v, __ATOMIC_RELAXED, __HIP_MEMORY_SCOPE_AGENT); }
; #define XB_SPIN(cond, bar) do { unsigned _sp = 0; while (cond) { __builtin_amdgcn_s_sleep(1); \
;     if ((++_sp & 255u) == 0u) { if (xb_ld(&(bar)[XB_TMO])) break; if (_sp > XB_SPIN_CAP) { atomicAdd(&(bar)[XB_TMO], 1u); break; } } } } while (0)
; #define SEAM_LOCAL() do { if (__builtin_amdgcn_readfirstlane((int)lds_word((unsigned)(__UINTPTR_TYPE__)lds + MISC_OFF + 68))) xcd_local_barrier(bar, 32u); else xcd_barrier(bar); } while (0)
; __device__ __forceinline__ void xcd_local_barrier(const XcdBarrier& b, unsigned nloc) {
;     asm volatile("s_waitcnt vmcnt(0)" ::: "memory");
;     __syncthreads();
;     if (threadIdx.x == 0) {
;         unsigned* bar = b.bar;
;         __builtin_amdgcn_s_waitcnt(0);
;         const unsigned old = xb_add(&bar[XB_LSUB(b.x)], 1u);
;         const unsigned gen = old / nloc;
;         if (old + 1u == (gen + 1u) * nloc) xb_add(&bar[XB_LGEN(b.x)], 1u);
;         else XB_SPIN(xb_ld(&bar[XB_LGEN(b.x)]) == gen, bar);
;         __builtin_amdgcn_fence(__ATOMIC_ACQUIRE, "agent");
;         asm volatile("s_waitcnt vmcnt(0)" ::: "memory");
;     }
;     __syncthreads();
; }
; __global__ void __launch_bounds__(512, 2) trunk_fwd(Args args) {
;     ...
;             __builtin_amdgcn_s_setprio(0);
;         }
;         SEAM_LOCAL();
.LBB0_975:
	s_setprio 0
	v_readlane_b32 s0, v254, 60
	v_mov_b32 v0, s0
	ds_read_b32 v0, v0
	s_waitcnt lgkmcnt(0)
	s_nop 0
	v_readfirstlane_b32 s0, v0
	s_cmp_eq_u32 s0, 0
	s_cbranch_scc1 .LBB0_989
	s_nop 0
	s_waitcnt lgkmcnt(0)
	s_barrier
	v_readlane_b32 s50, v255, 5
	v_readlane_b32 s51, v255, 6
	s_branch .LBB0_1049
